# v18 + HGRN pass-2 per-head norm: 8-lane sum via three DPP adds (quad_perm, row_half_mirror) instead of three ds_bpermute LDS round trips
# baseline (speedup 1.0000x reference)
.LBB0_872:
	v_lshlrev_b32_e32 v38, 16, v20
	v_and_b32_e32 v39, 0xffff0000, v20
	v_lshlrev_b32_e32 v40, 16, v21
	v_and_b32_e32 v41, 0xffff0000, v21
	v_lshlrev_b32_e32 v34, 16, v22
	v_and_b32_e32 v35, 0xffff0000, v22
	v_lshlrev_b32_e32 v36, 16, v23
	v_and_b32_e32 v37, 0xffff0000, v23
	ds_write_b128 v208, v[24:27] offset:34816
	s_waitcnt lgkmcnt(0)
	s_barrier
	global_load_dwordx4 v[20:23], v[128:129], off offset:16
	global_load_dwordx4 v[28:31], v[128:129], off
	ds_read_b128 v[24:27], v207 offset:34816
	v_lshlrev_b32_e32 v32, 16, v16
	v_and_b32_e32 v33, 0xffff0000, v16
	v_lshlrev_b32_e32 v52, 16, v17
	v_and_b32_e32 v53, 0xffff0000, v17
	v_lshlrev_b32_e32 v54, 16, v18
	v_and_b32_e32 v55, 0xffff0000, v18
	v_lshlrev_b32_e32 v142, 16, v19
	v_and_b32_e32 v143, 0xffff0000, v19
	ds_read_b128 v[16:19], v207 offset:34832
	ds_read_b128 v[44:47], v207 offset:34848
	ds_read_b128 v[48:51], v207 offset:34864
	s_waitcnt lgkmcnt(3)
	v_pk_add_f32 v[144:145], v[26:27], v[40:41]
	v_pk_add_f32 v[146:147], v[24:25], v[38:39]
	v_pk_mul_f32 v[24:25], v[144:145], v[144:145]
	v_pk_mul_f32 v[26:27], v[146:147], v[146:147]
	s_waitcnt lgkmcnt(2)
	v_pk_add_f32 v[42:43], v[18:19], v[36:37]
	v_pk_mov_b32 v[38:39], v[26:27], v[24:25] op_sel:[1,0]
	v_mov_b32_e32 v27, v25
	v_pk_add_f32 v[148:149], v[38:39], v[26:27]
	v_pk_add_f32 v[150:151], v[16:17], v[34:35]
	global_load_dwordx4 v[16:19], v[128:129], off offset:48
	global_load_dwordx4 v[24:27], v[128:129], off offset:32
	v_pk_mul_f32 v[34:35], v[42:43], v[42:43]
	v_pk_mul_f32 v[36:37], v[150:151], v[150:151]
	s_waitcnt lgkmcnt(1)
	v_pk_add_f32 v[40:41], v[44:45], v[32:33]
	v_pk_mov_b32 v[38:39], v[36:37], v[34:35] op_sel:[1,0]
	v_mov_b32_e32 v37, v35
	v_pk_add_f32 v[36:37], v[38:39], v[36:37]
	s_waitcnt lgkmcnt(0)
	v_pk_add_f32 v[34:35], v[48:49], v[54:55]
	v_pk_add_f32 v[38:39], v[46:47], v[52:53]
	v_mul_f32_e32 v1, v34, v34
	v_mul_f32_e32 v46, v35, v35
	v_pk_add_f32 v[44:45], v[148:149], v[148:149] op_sel:[0,1] op_sel_hi:[1,0]
	v_pk_add_f32 v[36:37], v[36:37], v[36:37] op_sel:[0,1] op_sel_hi:[1,0]
	v_mov_b32_e32 v45, v1
	v_mov_b32_e32 v37, v46
	v_pk_add_f32 v[32:33], v[50:51], v[142:143]
	v_pk_add_f32 v[36:37], v[44:45], v[36:37]
	v_mul_f32_e32 v44, v41, v41
	v_mul_f32_e32 v47, v32, v32
	v_pk_fma_f32 v[44:45], v[40:41], v[40:41], v[44:45] op_sel_hi:[1,1,0]
	v_mul_f32_e32 v46, v39, v39
	v_mul_f32_e32 v48, v33, v33
	v_mov_b32_e32 v45, v47
	v_pk_fma_f32 v[46:47], v[38:39], v[38:39], v[46:47] op_sel_hi:[1,1,0]
	s_or_b32 s12, s3, 0x1e0000
	v_mov_b32_e32 v47, v48
	v_pk_add_f32 v[44:45], v[44:45], v[46:47]
	v_and_b32_e32 v47, 0xffff0000, v12
	v_pk_add_f32 v[36:37], v[36:37], v[44:45]
	v_lshlrev_b32_e32 v46, 16, v12
	v_add_f32_e32 v1, v36, v37
	s_nop 1
	v_lshlrev_b64 v[2:3], 11, v[2:3]
	s_waitcnt lgkmcnt(0)
	v_add_f32_dpp v1, v1, v1 quad_perm:[1,0,3,2] row_mask:0xf bank_mask:0xf
	s_nop 1
	s_waitcnt lgkmcnt(0)
	v_add_f32_dpp v1, v1, v1 quad_perm:[2,3,0,1] row_mask:0xf bank_mask:0xf
	s_nop 1
	s_waitcnt lgkmcnt(0)
	v_add_f32_dpp v1, v1, v1 row_half_mirror row_mask:0xf bank_mask:0xf
	v_fmamk_f32 v1, v1, 0x3c000000, v181
	v_mul_f32_e32 v36, 0x4b800000, v1
	v_cmp_gt_f32_e32 vcc, s92, v1
	s_nop 1
	v_cndmask_b32_e32 v1, v1, v36, vcc
	v_rsq_f32_e32 v1, v1
	v_lshl_add_u64 v[36:37], s[4:5], 1, v[62:63]
	v_readlane_b32 s4, v254, 40
	s_add_i32 s95, s95, s4
	v_mul_f32_e32 v44, 0x45800000, v1
	v_cndmask_b32_e32 v44, v1, v44, vcc
	v_pk_mul_f32 v[48:49], v[146:147], v[44:45] op_sel_hi:[1,0]
	s_add_i32 s94, s94, s4
	s_waitcnt vmcnt(2)
	v_pk_mul_f32 v[28:29], v[28:29], v[48:49]
	s_cmpk_gt_i32 s95, 0xff
	v_pk_mul_f32 v[28:29], v[28:29], v[46:47]
	v_and_b32_e32 v47, 0xffff0000, v13
	v_lshlrev_b32_e32 v46, 16, v13
	v_pk_mul_f32 v[12:13], v[144:145], v[44:45] op_sel_hi:[1,0]
	v_readlane_b32 s5, v254, 41
	v_pk_mul_f32 v[12:13], v[30:31], v[12:13]
	s_nop 0
	v_pk_mul_f32 v[30:31], v[12:13], v[46:47]
	v_cvt_pk_bf16_f32 v12, v28, v29
	v_cvt_pk_bf16_f32 v13, v30, v31
	v_pk_mul_f32 v[30:31], v[150:151], v[44:45] op_sel_hi:[1,0]
	v_and_b32_e32 v29, 0xffff0000, v14
	v_lshlrev_b32_e32 v28, 16, v14
	v_pk_mul_f32 v[20:21], v[20:21], v[30:31]
	s_nop 0
	v_pk_mul_f32 v[20:21], v[20:21], v[28:29]
	v_and_b32_e32 v29, 0xffff0000, v15
	v_lshlrev_b32_e32 v28, 16, v15
	v_pk_mul_f32 v[14:15], v[42:43], v[44:45] op_sel_hi:[1,0]
	s_nop 0
	v_pk_mul_f32 v[14:15], v[22:23], v[14:15]
	s_nop 0
	v_pk_mul_f32 v[22:23], v[14:15], v[28:29]
	v_cvt_pk_bf16_f32 v14, v20, v21
	v_cvt_pk_bf16_f32 v15, v22, v23
	v_pk_mul_f32 v[22:23], v[40:41], v[44:45] op_sel_hi:[1,0]
	v_and_b32_e32 v21, 0xffff0000, v8
	v_lshlrev_b32_e32 v20, 16, v8
	s_waitcnt vmcnt(0)
	v_pk_mul_f32 v[22:23], v[24:25], v[22:23]
	s_nop 0
	v_pk_mul_f32 v[20:21], v[22:23], v[20:21]
	v_and_b32_e32 v23, 0xffff0000, v9
	v_lshlrev_b32_e32 v22, 16, v9
	v_pk_mul_f32 v[8:9], v[38:39], v[44:45] op_sel_hi:[1,0]
	s_nop 0
	v_pk_mul_f32 v[8:9], v[26:27], v[8:9]
	s_nop 0
	v_pk_mul_f32 v[22:23], v[8:9], v[22:23]
	v_cvt_pk_bf16_f32 v8, v20, v21
	v_cvt_pk_bf16_f32 v9, v22, v23
	v_pk_mul_f32 v[22:23], v[34:35], v[44:45] op_sel_hi:[1,0]
	v_and_b32_e32 v21, 0xffff0000, v10
	v_lshlrev_b32_e32 v20, 16, v10
	v_pk_mul_f32 v[16:17], v[16:17], v[22:23]
	s_nop 0
	v_pk_mul_f32 v[16:17], v[16:17], v[20:21]
	v_and_b32_e32 v21, 0xffff0000, v11
	v_lshlrev_b32_e32 v20, 16, v11
	v_pk_mul_f32 v[10:11], v[32:33], v[44:45] op_sel_hi:[1,0]
	s_nop 0
	v_pk_mul_f32 v[10:11], v[18:19], v[10:11]
	s_nop 0
	v_pk_mul_f32 v[18:19], v[10:11], v[20:21]
	v_cvt_pk_bf16_f32 v10, v16, v17
	v_lshl_add_u64 v[16:17], v[36:37], 0, s[12:13]
	v_lshl_add_u64 v[2:3], v[16:17], 0, v[2:3]
	v_cvt_pk_bf16_f32 v11, v18, v19
	global_store_dwordx4 v[2:3], v[12:15], off
	global_store_dwordx4 v[2:3], v[8:11], off offset:16
	s_barrier
	s_cbranch_scc1 .LBB0_908

.LBB0_896:
	v_add_u32_e32 v208, s74, v141
	v_lshlrev_b32_e32 v148, 16, v44
	v_and_b32_e32 v149, 0xffff0000, v44
	v_lshlrev_b32_e32 v150, 16, v45
	v_and_b32_e32 v151, 0xffff0000, v45
	v_lshlrev_b32_e32 v152, 16, v46
	v_and_b32_e32 v153, 0xffff0000, v46
	v_lshlrev_b32_e32 v154, 16, v47
	v_and_b32_e32 v155, 0xffff0000, v47
	v_lshlrev_b32_e32 v210, 16, v40
	v_and_b32_e32 v211, 0xffff0000, v40
	v_lshlrev_b32_e32 v212, 16, v41
	v_and_b32_e32 v213, 0xffff0000, v41
	v_lshlrev_b32_e32 v214, 16, v42
	v_and_b32_e32 v215, 0xffff0000, v42
	v_lshlrev_b32_e32 v216, 16, v43
	v_and_b32_e32 v217, 0xffff0000, v43
	ds_write_b128 v208, v[48:51] offset:34816
	s_waitcnt lgkmcnt(0)
	s_barrier
	ds_read_b128 v[40:43], v207 offset:34816
	ds_read_b128 v[44:47], v207 offset:34832
	ds_read_b128 v[48:51], v207 offset:34848
	ds_read_b128 v[52:55], v207 offset:34864
	v_lshl_add_u64 v[146:147], v[146:147], 0, s[56:57]
	s_waitcnt lgkmcnt(3)
	v_pk_add_f32 v[162:163], v[42:43], v[150:151]
	v_pk_add_f32 v[164:165], v[40:41], v[148:149]
	v_pk_mul_f32 v[40:41], v[162:163], v[162:163]
	v_pk_mul_f32 v[42:43], v[164:165], v[164:165]
	s_waitcnt lgkmcnt(2)
	v_pk_add_f32 v[156:157], v[46:47], v[154:155]
	v_pk_mov_b32 v[148:149], v[42:43], v[40:41] op_sel:[1,0]
	v_mov_b32_e32 v43, v41
	v_pk_add_f32 v[160:161], v[44:45], v[152:153]
	v_pk_add_f32 v[40:41], v[148:149], v[42:43]
	v_pk_mul_f32 v[42:43], v[156:157], v[156:157]
	v_pk_mul_f32 v[44:45], v[160:161], v[160:161]
	s_waitcnt lgkmcnt(0)
	v_pk_add_f32 v[150:151], v[52:53], v[214:215]
	v_pk_mov_b32 v[46:47], v[44:45], v[42:43] op_sel:[1,0]
	v_mov_b32_e32 v45, v43
	v_pk_add_f32 v[42:43], v[46:47], v[44:45]
	v_mul_f32_e32 v44, v150, v150
	v_mul_f32_e32 v45, v151, v151
	v_pk_add_f32 v[40:41], v[40:41], v[40:41] op_sel:[0,1] op_sel_hi:[1,0]
	v_pk_add_f32 v[42:43], v[42:43], v[42:43] op_sel:[0,1] op_sel_hi:[1,0]
	v_pk_add_f32 v[152:153], v[50:51], v[212:213]
	v_pk_add_f32 v[154:155], v[48:49], v[210:211]
	v_mov_b32_e32 v41, v44
	v_mov_b32_e32 v43, v45
	v_pk_add_f32 v[148:149], v[54:55], v[216:217]
	v_pk_add_f32 v[40:41], v[40:41], v[42:43]
	v_mul_f32_e32 v42, v155, v155
	v_mul_f32_e32 v44, v153, v153
	v_mul_f32_e32 v46, v148, v148
	v_mul_f32_e32 v47, v149, v149
	v_pk_fma_f32 v[42:43], v[154:155], v[154:155], v[42:43] op_sel_hi:[1,1,0]
	v_pk_fma_f32 v[44:45], v[152:153], v[152:153], v[44:45] op_sel_hi:[1,1,0]
	v_mov_b32_e32 v43, v46
	v_mov_b32_e32 v45, v47
	v_pk_add_f32 v[42:43], v[42:43], v[44:45]
	v_and_b32_e32 v211, 0xffff0000, v36
	v_pk_add_f32 v[40:41], v[40:41], v[42:43]
	v_lshlrev_b32_e32 v210, 16, v36
	v_add_f32_e32 v40, v40, v41
	s_nop 1
	s_waitcnt lgkmcnt(0)
	v_add_f32_dpp v40, v40, v40 quad_perm:[1,0,3,2] row_mask:0xf bank_mask:0xf
	s_nop 1
	s_waitcnt lgkmcnt(0)
	v_add_f32_dpp v40, v40, v40 quad_perm:[2,3,0,1] row_mask:0xf bank_mask:0xf
	s_nop 1
	s_waitcnt lgkmcnt(0)
	v_add_f32_dpp v40, v40, v40 row_half_mirror row_mask:0xf bank_mask:0xf
	v_fmamk_f32 v40, v40, 0x3c000000, v181
	v_cmp_gt_f32_e32 vcc, s92, v40
	v_mul_f32_e32 v41, 0x4b800000, v40
	s_nop 0
	v_cndmask_b32_e32 v40, v40, v41, vcc
	v_rsq_f32_e32 v40, v40
	s_nop 0
	v_mul_f32_e32 v41, 0x45800000, v40
	v_cndmask_b32_e32 v158, v40, v41, vcc
	global_load_dwordx4 v[40:43], v[128:129], off offset:48
	global_load_dwordx4 v[44:47], v[128:129], off offset:32
	global_load_dwordx4 v[48:51], v[128:129], off offset:16
	global_load_dwordx4 v[52:55], v[128:129], off
	v_pk_mul_f32 v[164:165], v[164:165], v[158:159] op_sel_hi:[1,0]
	s_waitcnt vmcnt(0)
	v_pk_mul_f32 v[52:53], v[52:53], v[164:165]
	v_and_b32_e32 v165, 0xffff0000, v37
	v_lshlrev_b32_e32 v164, 16, v37
	v_pk_mul_f32 v[36:37], v[162:163], v[158:159] op_sel_hi:[1,0]
	v_pk_mul_f32 v[52:53], v[52:53], v[210:211]
	v_pk_mul_f32 v[36:37], v[54:55], v[36:37]
	s_nop 0
	v_pk_mul_f32 v[54:55], v[36:37], v[164:165]
	v_cvt_pk_bf16_f32 v36, v52, v53
	v_cvt_pk_bf16_f32 v37, v54, v55
	v_pk_mul_f32 v[54:55], v[160:161], v[158:159] op_sel_hi:[1,0]
	v_and_b32_e32 v53, 0xffff0000, v38
	v_lshlrev_b32_e32 v52, 16, v38
	v_pk_mul_f32 v[48:49], v[48:49], v[54:55]
	s_nop 0
	v_pk_mul_f32 v[48:49], v[48:49], v[52:53]
	v_and_b32_e32 v53, 0xffff0000, v39
	v_lshlrev_b32_e32 v52, 16, v39
	v_pk_mul_f32 v[38:39], v[156:157], v[158:159] op_sel_hi:[1,0]
	s_nop 0
	v_pk_mul_f32 v[38:39], v[50:51], v[38:39]
	s_nop 0
	v_pk_mul_f32 v[50:51], v[38:39], v[52:53]
	v_cvt_pk_bf16_f32 v38, v48, v49
	v_cvt_pk_bf16_f32 v39, v50, v51
	v_pk_mul_f32 v[50:51], v[154:155], v[158:159] op_sel_hi:[1,0]
	v_and_b32_e32 v49, 0xffff0000, v32
	v_lshlrev_b32_e32 v48, 16, v32
	v_pk_mul_f32 v[44:45], v[44:45], v[50:51]
	s_nop 0
	v_pk_mul_f32 v[44:45], v[44:45], v[48:49]
	v_and_b32_e32 v49, 0xffff0000, v33
	v_lshlrev_b32_e32 v48, 16, v33
	v_pk_mul_f32 v[32:33], v[152:153], v[158:159] op_sel_hi:[1,0]
	s_nop 0
	v_pk_mul_f32 v[32:33], v[46:47], v[32:33]
	s_nop 0
	v_pk_mul_f32 v[46:47], v[32:33], v[48:49]
	v_cvt_pk_bf16_f32 v32, v44, v45
	v_cvt_pk_bf16_f32 v33, v46, v47
	v_pk_mul_f32 v[46:47], v[150:151], v[158:159] op_sel_hi:[1,0]
	v_and_b32_e32 v45, 0xffff0000, v34
	v_lshlrev_b32_e32 v44, 16, v34
	v_pk_mul_f32 v[40:41], v[40:41], v[46:47]
	s_nop 0
	v_pk_mul_f32 v[40:41], v[40:41], v[44:45]
	v_and_b32_e32 v45, 0xffff0000, v35
	v_lshlrev_b32_e32 v44, 16, v35
	v_pk_mul_f32 v[34:35], v[148:149], v[158:159] op_sel_hi:[1,0]
	s_nop 0
	v_pk_mul_f32 v[34:35], v[42:43], v[34:35]
	s_nop 0
	v_pk_mul_f32 v[42:43], v[34:35], v[44:45]
	v_cvt_pk_bf16_f32 v34, v40, v41
	v_lshl_add_u64 v[40:41], v[142:143], 0, s[6:7]
	s_add_u32 s6, s6, 0x20000
	v_add_co_u32_e32 v40, vcc, s93, v40
	s_addc_u32 s7, s7, 0
	s_nop 0
	v_addc_co_u32_e32 v41, vcc, 0, v41, vcc
	s_cmp_eq_u32 s6, 0x1e0000
	v_cvt_pk_bf16_f32 v35, v42, v43
	global_store_dwordx4 v[40:41], v[36:39], off
	global_store_dwordx4 v[40:41], v[32:35], off offset:16
	s_cbranch_scc1 .LBB0_900
	v_mov_b64_e32 v[46:47], v[22:23]
	v_mov_b64_e32 v[42:43], v[18:19]
	v_mov_b64_e32 v[38:39], v[14:15]
	v_mov_b64_e32 v[34:35], v[10:11]
	v_mov_b64_e32 v[44:45], v[20:21]
	v_mov_b64_e32 v[40:41], v[16:17]
	v_mov_b64_e32 v[36:37], v[12:13]
	v_mov_b64_e32 v[32:33], v[8:9]
	s_branch .LBB0_886
